# GU K-loop LDS-DMA pieces rebalanced 2/6/2/6 -> 4/4/4/4 per load segment (A half-0 pieces issued one segment later, waits 8/6/8/6)
# baseline (speedup 1.0000x reference)
; #define PG8_STAGE(bufoff, gbase, voff) do { _Pragma("unroll") for (int _i = 0; _i < 2; ++_i) \
;         __builtin_amdgcn_global_load_lds((const unsigned*)((const char*)(gbase) + (voff)[_i]), (PG8_LAS unsigned*)(lds + (bufoff) + ldsw + _i * 8192), 16, 0, 0); } while (0)
; #define PG8_LDA(dst, b, h) do { _Pragma("unroll") for (int m = 0; m < 4; ++m) _Pragma("unroll") for (int k = 0; k < 2; ++k) dst[m][k] = *(const PG8_LAS bf16x8*)(lds + PG8_SA(b, h) + aoff + m * 2048 + k * 1024); } while (0)
; #define PG8_LDB(dst, b, h) do { _Pragma("unroll") for (int n = 0; n < 2; ++n) _Pragma("unroll") for (int k = 0; k < 2; ++k) dst[n][k] = *(const PG8_LAS bf16x8*)(lds + PG8_SB(b, h) + boff + n * 2048 + k * 1024); } while (0)
; #define PG8_MMA(ai, bj, At, Bt) do { __builtin_amdgcn_s_setprio(1); _Pragma("unroll") for (int m = 0; m < 4; ++m) _Pragma("unroll") for (int n = 0; n < 2; ++n) _Pragma("unroll") for (int k = 0; k < 2; ++k) \
;         acc[ai][bj][m][n] = __builtin_amdgcn_mfma_f32_16x16x32_bf16(Bt[n][k], At[m][k], acc[ai][bj][m][n], 0, 0, 0); __builtin_amdgcn_s_setprio(0); } while (0)
; #define PG8_WAIT_V(n) asm volatile("s_waitcnt vmcnt(" #n ")" ::: "memory")
; #define PG8_WAIT_L(n) asm volatile("s_waitcnt lgkmcnt(" #n ")" ::: "memory")
; #define PG8_BAR __builtin_amdgcn_s_barrier()
; #define PG8_SCHED __builtin_amdgcn_sched_barrier(0)
; template <class Epi, class Sched, bool ALIGN_EPI = false, bool SP2 = false>
; __device__ __forceinline__ void gemm_phase(PG8_LAS unsigned char* lds, const Gemm g, const Sched& S, const Epi& E) {
;     ...
;             PG8_LDB(B0, 0, 0); PG8_LDB(B1, 0, 1); PG8_SCHED; PG8_LDA(At, 0, 0); PG8_STAGE(PG8_SA(1, 1), a1 + hstep, voffA);
;             PG8_WAIT_V(8); PG8_WAIT_L(0); PG8_BAR; PG8_MMA(0, 0, At, B0); PG8_MMA(0, 1, At, B1); PG8_BAR; PG8_SCHED;
;             PG8_LDA(At, 0, 1); PG8_STAGE(PG8_SB(0, 0), b2, voffB); PG8_STAGE(PG8_SB(0, 1), b2 + hstep, voffB); PG8_STAGE(PG8_SA(0, 0), a2, voffA);
;             PG8_WAIT_V(8); PG8_WAIT_L(0); PG8_BAR; PG8_MMA(1, 0, At, B0); PG8_MMA(1, 1, At, B1); PG8_BAR; PG8_SCHED;
.LBB0_1647:
	s_add_u32 s6, s4, 0xfffc0080
	s_addc_u32 s7, s5, -1
	s_and_b64 s[0:1], s[0:1], exec
	s_cselect_b32 s7, s39, s7
	s_cselect_b32 s6, s47, s6
	s_cselect_b32 s1, s53, s56
	s_cselect_b32 s0, s54, s55
	s_add_i32 s58, 0, 0x10000
	v_add_u32_e32 v162, s58, v165
	s_add_i32 s60, 0, 0x14000
	ds_read_b128 v[132:135], v162
	ds_read_b128 v[136:139], v162 offset:1024
	ds_read_b128 v[140:143], v162 offset:2048
	ds_read_b128 v[180:183], v162 offset:3072
	v_add_u32_e32 v162, s60, v165
	ds_read_b128 v[200:203], v162
	ds_read_b128 v[204:207], v162 offset:1024
	ds_read_b128 v[208:211], v162 offset:2048
	ds_read_b128 v[212:215], v162 offset:3072
	s_add_u32 vcc_lo, s4, 0xfffc0000
	s_addc_u32 vcc_hi, s5, -1
	v_lshl_add_u64 v[184:185], vcc, 0, v[154:155]
	v_lshl_add_u64 v[186:187], vcc, 0, v[152:153]
	v_lshl_add_u64 v[168:169], s[4:5], 0, v[158:159]
	v_lshl_add_u64 v[188:189], s[4:5], 0, v[160:161]
	s_mov_b32 m0, s31
	ds_read_b128 v[216:219], v197
	ds_read_b128 v[220:223], v197 offset:1024
	ds_read_b128 v[224:227], v197 offset:2048
	ds_read_b128 v[228:231], v197 offset:3072
	ds_read_b128 v[232:235], v197 offset:4096
	ds_read_b128 v[236:239], v197 offset:5120
	ds_read_b128 v[240:243], v197 offset:6144
	ds_read_b128 v[244:247], v197 offset:7168
	global_load_lds_dwordx4 v[184:185], off
	s_mov_b32 m0, s34
	s_nop 0
	global_load_lds_dwordx4 v[186:187], off
	s_add_i32 m0, s27, 0xc000
	s_nop 0
	global_load_lds_dwordx4 v[168:169], off
	s_add_i32 m0, s27, 0xe000
	s_nop 0
	global_load_lds_dwordx4 v[188:189], off
	s_waitcnt vmcnt(8)
	s_waitcnt lgkmcnt(0)
	s_setprio 1
	s_barrier
	v_mfma_f32_16x16x32_bf16 v[124:127], v[132:135], v[216:219], v[124:127]
	v_mfma_f32_16x16x32_bf16 v[116:119], v[140:143], v[216:219], v[116:119]
	v_mfma_f32_16x16x32_bf16 v[108:111], v[132:135], v[224:227], v[108:111]
	v_mfma_f32_16x16x32_bf16 v[100:103], v[140:143], v[224:227], v[100:103]
	v_mfma_f32_16x16x32_bf16 v[92:95], v[132:135], v[232:235], v[92:95]
	v_mfma_f32_16x16x32_bf16 v[84:87], v[140:143], v[232:235], v[84:87]
	v_mfma_f32_16x16x32_bf16 v[76:79], v[132:135], v[240:243], v[76:79]
	v_mfma_f32_16x16x32_bf16 v[68:71], v[140:143], v[240:243], v[68:71]
	v_mfma_f32_16x16x32_bf16 v[124:127], v[136:139], v[220:223], v[124:127]
	v_mfma_f32_16x16x32_bf16 v[116:119], v[180:183], v[220:223], v[116:119]
	v_mfma_f32_16x16x32_bf16 v[108:111], v[136:139], v[228:231], v[108:111]
	v_mfma_f32_16x16x32_bf16 v[100:103], v[180:183], v[228:231], v[100:103]
	v_mfma_f32_16x16x32_bf16 v[92:95], v[136:139], v[236:239], v[92:95]
	v_mfma_f32_16x16x32_bf16 v[84:87], v[180:183], v[236:239], v[84:87]
	v_mfma_f32_16x16x32_bf16 v[76:79], v[136:139], v[244:247], v[76:79]
	v_mfma_f32_16x16x32_bf16 v[68:71], v[180:183], v[244:247], v[68:71]
	s_setprio 0
	s_setprio 1
	v_mfma_f32_16x16x32_bf16 v[120:123], v[200:203], v[216:219], v[120:123]
	v_mfma_f32_16x16x32_bf16 v[112:115], v[208:211], v[216:219], v[112:115]
	v_mfma_f32_16x16x32_bf16 v[104:107], v[200:203], v[224:227], v[104:107]
	v_mfma_f32_16x16x32_bf16 v[96:99], v[208:211], v[224:227], v[96:99]
	v_mfma_f32_16x16x32_bf16 v[88:91], v[200:203], v[232:235], v[88:91]
	v_mfma_f32_16x16x32_bf16 v[80:83], v[208:211], v[232:235], v[80:83]
	v_mfma_f32_16x16x32_bf16 v[72:75], v[200:203], v[240:243], v[72:75]
	v_mfma_f32_16x16x32_bf16 v[64:67], v[208:211], v[240:243], v[64:67]
	v_mfma_f32_16x16x32_bf16 v[120:123], v[204:207], v[220:223], v[120:123]
	v_mfma_f32_16x16x32_bf16 v[112:115], v[212:215], v[220:223], v[112:115]
	v_mfma_f32_16x16x32_bf16 v[104:107], v[204:207], v[228:231], v[104:107]
	v_mfma_f32_16x16x32_bf16 v[96:99], v[212:215], v[228:231], v[96:99]
	v_mfma_f32_16x16x32_bf16 v[88:91], v[204:207], v[236:239], v[88:91]
	v_mfma_f32_16x16x32_bf16 v[80:83], v[212:215], v[236:239], v[80:83]
	v_mfma_f32_16x16x32_bf16 v[72:75], v[204:207], v[244:247], v[72:75]
	v_mfma_f32_16x16x32_bf16 v[64:67], v[212:215], v[244:247], v[64:67]
	s_barrier
	s_setprio 0
	s_add_i32 s58, s58, s26
	v_lshl_add_u64 v[168:169], s[0:1], 0, v[144:145]
	s_mov_b32 m0, s58
	ds_read_b128 v[216:219], v197 offset:16384
	ds_read_b128 v[220:223], v197 offset:17408
	ds_read_b128 v[224:227], v197 offset:18432
	ds_read_b128 v[228:231], v197 offset:19456
	ds_read_b128 v[232:235], v197 offset:20480
	ds_read_b128 v[236:239], v197 offset:21504
	ds_read_b128 v[240:243], v197 offset:22528
	ds_read_b128 v[244:247], v197 offset:23552
	global_load_lds_dwordx4 v[168:169], off
	s_add_i32 m0, s58, 0x2000
	s_add_u32 s58, s0, 0x40000
	v_lshl_add_u64 v[172:173], s[0:1], 0, v[150:151]
	s_addc_u32 s59, s1, 0
	s_add_i32 s60, s60, s26
	global_load_lds_dwordx4 v[172:173], off
	v_lshl_add_u64 v[184:185], s[58:59], 0, v[144:145]
	s_mov_b32 m0, s60
	s_nop 0
	global_load_lds_dwordx4 v[184:185], off
	v_lshl_add_u64 v[184:185], s[58:59], 0, v[150:151]
	s_add_i32 m0, s60, 0x2000
	s_nop 0
	global_load_lds_dwordx4 v[184:185], off
	s_waitcnt vmcnt(6)
	s_waitcnt lgkmcnt(0)
	s_setprio 1
	s_barrier
; #define PG8_STAGE(bufoff, gbase, voff) do { _Pragma("unroll") for (int _i = 0; _i < 2; ++_i) \
;         __builtin_amdgcn_global_load_lds((const unsigned*)((const char*)(gbase) + (voff)[_i]), (PG8_LAS unsigned*)(lds + (bufoff) + ldsw + _i * 8192), 16, 0, 0); } while (0)
; #define PG8_LDA(dst, b, h) do { _Pragma("unroll") for (int m = 0; m < 4; ++m) _Pragma("unroll") for (int k = 0; k < 2; ++k) dst[m][k] = *(const PG8_LAS bf16x8*)(lds + PG8_SA(b, h) + aoff + m * 2048 + k * 1024); } while (0)
; #define PG8_LDB(dst, b, h) do { _Pragma("unroll") for (int n = 0; n < 2; ++n) _Pragma("unroll") for (int k = 0; k < 2; ++k) dst[n][k] = *(const PG8_LAS bf16x8*)(lds + PG8_SB(b, h) + boff + n * 2048 + k * 1024); } while (0)
; #define PG8_MMA(ai, bj, At, Bt) do { __builtin_amdgcn_s_setprio(1); _Pragma("unroll") for (int m = 0; m < 4; ++m) _Pragma("unroll") for (int n = 0; n < 2; ++n) _Pragma("unroll") for (int k = 0; k < 2; ++k) \
;         acc[ai][bj][m][n] = __builtin_amdgcn_mfma_f32_16x16x32_bf16(Bt[n][k], At[m][k], acc[ai][bj][m][n], 0, 0, 0); __builtin_amdgcn_s_setprio(0); } while (0)
; #define PG8_WAIT_V(n) asm volatile("s_waitcnt vmcnt(" #n ")" ::: "memory")
; #define PG8_WAIT_L(n) asm volatile("s_waitcnt lgkmcnt(" #n ")" ::: "memory")
; #define PG8_BAR __builtin_amdgcn_s_barrier()
; #define PG8_SCHED __builtin_amdgcn_sched_barrier(0)
; template <class Epi, class Sched, bool ALIGN_EPI = false, bool SP2 = false>
; __device__ __forceinline__ void gemm_phase(PG8_LAS unsigned char* lds, const Gemm g, const Sched& S, const Epi& E) {
;     ...
;             PG8_WAIT_V(8); PG8_WAIT_L(0); PG8_BAR; PG8_MMA(1, 0, At, B0); PG8_MMA(1, 1, At, B1); PG8_BAR; PG8_SCHED;
;             PG8_LDB(B0, 1, 0); PG8_LDB(B1, 1, 1); PG8_SCHED; PG8_LDA(At, 1, 0); PG8_STAGE(PG8_SA(0, 1), a2 + hstep, voffA);
;             PG8_WAIT_V(8); PG8_WAIT_L(0); PG8_BAR; PG8_MMA(0, 0, At, B0); PG8_MMA(0, 1, At, B1); PG8_BAR; PG8_SCHED;
	v_mfma_f32_16x16x32_bf16 v[60:63], v[132:135], v[216:219], v[60:63]
	v_mfma_f32_16x16x32_bf16 v[52:55], v[140:143], v[216:219], v[52:55]
	v_mfma_f32_16x16x32_bf16 v[44:47], v[132:135], v[224:227], v[44:47]
	v_mfma_f32_16x16x32_bf16 v[36:39], v[140:143], v[224:227], v[36:39]
	v_mfma_f32_16x16x32_bf16 v[28:31], v[132:135], v[232:235], v[28:31]
	v_mfma_f32_16x16x32_bf16 v[20:23], v[140:143], v[232:235], v[20:23]
	v_mfma_f32_16x16x32_bf16 v[12:15], v[132:135], v[240:243], v[12:15]
	v_mfma_f32_16x16x32_bf16 v[4:7], v[140:143], v[240:243], v[4:7]
	v_mfma_f32_16x16x32_bf16 v[60:63], v[136:139], v[220:223], v[60:63]
	v_mfma_f32_16x16x32_bf16 v[52:55], v[180:183], v[220:223], v[52:55]
	v_mfma_f32_16x16x32_bf16 v[44:47], v[136:139], v[228:231], v[44:47]
	v_mfma_f32_16x16x32_bf16 v[36:39], v[180:183], v[228:231], v[36:39]
	v_mfma_f32_16x16x32_bf16 v[28:31], v[136:139], v[236:239], v[28:31]
	v_mfma_f32_16x16x32_bf16 v[20:23], v[180:183], v[236:239], v[20:23]
	v_mfma_f32_16x16x32_bf16 v[12:15], v[136:139], v[244:247], v[12:15]
	v_mfma_f32_16x16x32_bf16 v[4:7], v[180:183], v[244:247], v[4:7]
	s_setprio 0
	s_setprio 1
	v_mfma_f32_16x16x32_bf16 v[56:59], v[200:203], v[216:219], v[56:59]
	v_mfma_f32_16x16x32_bf16 v[48:51], v[208:211], v[216:219], v[48:51]
	v_mfma_f32_16x16x32_bf16 v[40:43], v[200:203], v[224:227], v[40:43]
	v_mfma_f32_16x16x32_bf16 v[32:35], v[208:211], v[224:227], v[32:35]
	v_mfma_f32_16x16x32_bf16 v[24:27], v[200:203], v[232:235], v[24:27]
	v_mfma_f32_16x16x32_bf16 v[16:19], v[208:211], v[232:235], v[16:19]
	v_mfma_f32_16x16x32_bf16 v[8:11], v[200:203], v[240:243], v[8:11]
	v_mfma_f32_16x16x32_bf16 v[0:3], v[208:211], v[240:243], v[0:3]
	v_mfma_f32_16x16x32_bf16 v[56:59], v[204:207], v[220:223], v[56:59]
	v_mfma_f32_16x16x32_bf16 v[48:51], v[212:215], v[220:223], v[48:51]
	v_mfma_f32_16x16x32_bf16 v[40:43], v[204:207], v[228:231], v[40:43]
	v_mfma_f32_16x16x32_bf16 v[32:35], v[212:215], v[228:231], v[32:35]
	v_mfma_f32_16x16x32_bf16 v[24:27], v[204:207], v[236:239], v[24:27]
	v_mfma_f32_16x16x32_bf16 v[16:19], v[212:215], v[236:239], v[16:19]
	v_mfma_f32_16x16x32_bf16 v[8:11], v[204:207], v[244:247], v[8:11]
	v_mfma_f32_16x16x32_bf16 v[0:3], v[212:215], v[244:247], v[0:3]
	s_barrier
	s_setprio 0
	s_add_i32 s58, 0, 0x18000
	v_add_u32_e32 v162, s58, v165
	s_add_i32 s59, 0, 0x1c000
	ds_read_b128 v[132:135], v162
	ds_read_b128 v[136:139], v162 offset:1024
	ds_read_b128 v[140:143], v162 offset:2048
	ds_read_b128 v[180:183], v162 offset:3072
	v_add_u32_e32 v162, s59, v165
	ds_read_b128 v[200:203], v162
	ds_read_b128 v[204:207], v162 offset:1024
	ds_read_b128 v[208:211], v162 offset:2048
	ds_read_b128 v[212:215], v162 offset:3072
	v_lshl_add_u64 v[184:185], s[6:7], 0, v[154:155]
	v_lshl_add_u64 v[186:187], s[6:7], 0, v[152:153]
	s_add_u32 s6, s6, 0x40000
	s_addc_u32 s7, s7, 0
	s_mov_b32 m0, s27
	v_lshl_add_u64 v[188:189], s[6:7], 0, v[154:155]
	ds_read_b128 v[216:219], v197 offset:32768
	ds_read_b128 v[220:223], v197 offset:33792
	ds_read_b128 v[224:227], v197 offset:34816
	ds_read_b128 v[228:231], v197 offset:35840
	ds_read_b128 v[232:235], v197 offset:36864
	ds_read_b128 v[236:239], v197 offset:37888
	ds_read_b128 v[240:243], v197 offset:38912
	ds_read_b128 v[244:247], v197 offset:39936
	global_load_lds_dwordx4 v[184:185], off
	s_mov_b32 m0, s28
	v_lshl_add_u64 v[184:185], s[6:7], 0, v[152:153]
	global_load_lds_dwordx4 v[186:187], off
	s_mov_b32 m0, s29
	s_nop 0
	global_load_lds_dwordx4 v[188:189], off
	s_mov_b32 m0, s30
	s_nop 0
	global_load_lds_dwordx4 v[184:185], off
	s_waitcnt vmcnt(8)
	s_waitcnt lgkmcnt(0)
	s_setprio 1
	s_barrier
; #define PG8_STAGE(bufoff, gbase, voff) do { _Pragma("unroll") for (int _i = 0; _i < 2; ++_i) \
;         __builtin_amdgcn_global_load_lds((const unsigned*)((const char*)(gbase) + (voff)[_i]), (PG8_LAS unsigned*)(lds + (bufoff) + ldsw + _i * 8192), 16, 0, 0); } while (0)
; #define PG8_LDA(dst, b, h) do { _Pragma("unroll") for (int m = 0; m < 4; ++m) _Pragma("unroll") for (int k = 0; k < 2; ++k) dst[m][k] = *(const PG8_LAS bf16x8*)(lds + PG8_SA(b, h) + aoff + m * 2048 + k * 1024); } while (0)
; #define PG8_MMA(ai, bj, At, Bt) do { __builtin_amdgcn_s_setprio(1); _Pragma("unroll") for (int m = 0; m < 4; ++m) _Pragma("unroll") for (int n = 0; n < 2; ++n) _Pragma("unroll") for (int k = 0; k < 2; ++k) \
;         acc[ai][bj][m][n] = __builtin_amdgcn_mfma_f32_16x16x32_bf16(Bt[n][k], At[m][k], acc[ai][bj][m][n], 0, 0, 0); __builtin_amdgcn_s_setprio(0); } while (0)
; #define PG8_WAIT_V(n) asm volatile("s_waitcnt vmcnt(" #n ")" ::: "memory")
; #define PG8_WAIT_L(n) asm volatile("s_waitcnt lgkmcnt(" #n ")" ::: "memory")
; #define PG8_BAR __builtin_amdgcn_s_barrier()
; #define PG8_SCHED __builtin_amdgcn_sched_barrier(0)
; template <class Epi, class Sched, bool ALIGN_EPI = false, bool SP2 = false>
; __device__ __forceinline__ void gemm_phase(PG8_LAS unsigned char* lds, const Gemm g, const Sched& S, const Epi& E) {
;     ...
;             PG8_WAIT_V(8); PG8_WAIT_L(0); PG8_BAR; PG8_MMA(0, 0, At, B0); PG8_MMA(0, 1, At, B1); PG8_BAR; PG8_SCHED;
;             PG8_LDA(At, 1, 1); PG8_STAGE(PG8_SB(1, 0), b3, voffB); PG8_STAGE(PG8_SB(1, 1), b3 + hstep, voffB); PG8_STAGE(PG8_SA(1, 0), a3, voffA);
;             PG8_WAIT_V(8); PG8_WAIT_L(0); PG8_BAR; PG8_MMA(1, 0, At, B0); PG8_MMA(1, 1, At, B1); PG8_BAR; PG8_SCHED;
	v_mfma_f32_16x16x32_bf16 v[124:127], v[132:135], v[216:219], v[124:127]
	v_mfma_f32_16x16x32_bf16 v[116:119], v[140:143], v[216:219], v[116:119]
	v_mfma_f32_16x16x32_bf16 v[108:111], v[132:135], v[224:227], v[108:111]
	v_mfma_f32_16x16x32_bf16 v[100:103], v[140:143], v[224:227], v[100:103]
	v_mfma_f32_16x16x32_bf16 v[92:95], v[132:135], v[232:235], v[92:95]
	v_mfma_f32_16x16x32_bf16 v[84:87], v[140:143], v[232:235], v[84:87]
	v_mfma_f32_16x16x32_bf16 v[76:79], v[132:135], v[240:243], v[76:79]
	v_mfma_f32_16x16x32_bf16 v[68:71], v[140:143], v[240:243], v[68:71]
	v_mfma_f32_16x16x32_bf16 v[124:127], v[136:139], v[220:223], v[124:127]
	v_mfma_f32_16x16x32_bf16 v[116:119], v[180:183], v[220:223], v[116:119]
	v_mfma_f32_16x16x32_bf16 v[108:111], v[136:139], v[228:231], v[108:111]
	v_mfma_f32_16x16x32_bf16 v[100:103], v[180:183], v[228:231], v[100:103]
	v_mfma_f32_16x16x32_bf16 v[92:95], v[136:139], v[236:239], v[92:95]
	v_mfma_f32_16x16x32_bf16 v[84:87], v[180:183], v[236:239], v[84:87]
	v_mfma_f32_16x16x32_bf16 v[76:79], v[136:139], v[244:247], v[76:79]
	v_mfma_f32_16x16x32_bf16 v[68:71], v[180:183], v[244:247], v[68:71]
	s_setprio 0
	s_setprio 1
	v_mfma_f32_16x16x32_bf16 v[120:123], v[200:203], v[216:219], v[120:123]
	v_mfma_f32_16x16x32_bf16 v[112:115], v[208:211], v[216:219], v[112:115]
	v_mfma_f32_16x16x32_bf16 v[104:107], v[200:203], v[224:227], v[104:107]
	v_mfma_f32_16x16x32_bf16 v[96:99], v[208:211], v[224:227], v[96:99]
	v_mfma_f32_16x16x32_bf16 v[88:91], v[200:203], v[232:235], v[88:91]
	v_mfma_f32_16x16x32_bf16 v[80:83], v[208:211], v[232:235], v[80:83]
	v_mfma_f32_16x16x32_bf16 v[72:75], v[200:203], v[240:243], v[72:75]
	v_mfma_f32_16x16x32_bf16 v[64:67], v[208:211], v[240:243], v[64:67]
	v_mfma_f32_16x16x32_bf16 v[120:123], v[204:207], v[220:223], v[120:123]
	v_mfma_f32_16x16x32_bf16 v[112:115], v[212:215], v[220:223], v[112:115]
	v_mfma_f32_16x16x32_bf16 v[104:107], v[204:207], v[228:231], v[104:107]
	v_mfma_f32_16x16x32_bf16 v[96:99], v[212:215], v[228:231], v[96:99]
	v_mfma_f32_16x16x32_bf16 v[88:91], v[204:207], v[236:239], v[88:91]
	v_mfma_f32_16x16x32_bf16 v[80:83], v[212:215], v[236:239], v[80:83]
	v_mfma_f32_16x16x32_bf16 v[72:75], v[204:207], v[244:247], v[72:75]
	v_mfma_f32_16x16x32_bf16 v[64:67], v[212:215], v[244:247], v[64:67]
	s_barrier
	s_setprio 0
	s_add_i32 s6, s58, s26
	v_lshl_add_u64 v[168:169], v[168:169], 0, s[94:95]
	s_mov_b32 m0, s6
	ds_read_b128 v[216:219], v197 offset:49152
	ds_read_b128 v[220:223], v197 offset:50176
	ds_read_b128 v[224:227], v197 offset:51200
	ds_read_b128 v[228:231], v197 offset:52224
	ds_read_b128 v[232:235], v197 offset:53248
	ds_read_b128 v[236:239], v197 offset:54272
	ds_read_b128 v[240:243], v197 offset:55296
	ds_read_b128 v[244:247], v197 offset:56320
	global_load_lds_dwordx4 v[168:169], off
	s_add_i32 m0, s6, 0x2000
	s_add_u32 s0, s0, 0x40080
	v_lshl_add_u64 v[168:169], v[172:173], 0, s[94:95]
	s_addc_u32 s1, s1, 0
	s_add_i32 s6, s59, s26
	global_load_lds_dwordx4 v[168:169], off
	v_lshl_add_u64 v[168:169], s[0:1], 0, v[144:145]
	s_mov_b32 m0, s6
	s_nop 0
	global_load_lds_dwordx4 v[168:169], off
	v_lshl_add_u64 v[168:169], s[0:1], 0, v[150:151]
	s_add_i32 m0, s6, 0x2000
	s_nop 0
	global_load_lds_dwordx4 v[168:169], off
	s_waitcnt vmcnt(6)
	s_waitcnt lgkmcnt(0)
	s_setprio 1
	s_barrier
	v_mfma_f32_16x16x32_bf16 v[60:63], v[132:135], v[216:219], v[60:63]
	v_mfma_f32_16x16x32_bf16 v[52:55], v[140:143], v[216:219], v[52:55]
	v_mfma_f32_16x16x32_bf16 v[44:47], v[132:135], v[224:227], v[44:47]
	v_mfma_f32_16x16x32_bf16 v[36:39], v[140:143], v[224:227], v[36:39]
	v_mfma_f32_16x16x32_bf16 v[28:31], v[132:135], v[232:235], v[28:31]
	v_mfma_f32_16x16x32_bf16 v[20:23], v[140:143], v[232:235], v[20:23]
	v_mfma_f32_16x16x32_bf16 v[12:15], v[132:135], v[240:243], v[12:15]
	v_mfma_f32_16x16x32_bf16 v[4:7], v[140:143], v[240:243], v[4:7]
	v_mfma_f32_16x16x32_bf16 v[60:63], v[136:139], v[220:223], v[60:63]
	v_mfma_f32_16x16x32_bf16 v[52:55], v[180:183], v[220:223], v[52:55]
	v_mfma_f32_16x16x32_bf16 v[44:47], v[136:139], v[228:231], v[44:47]
	v_mfma_f32_16x16x32_bf16 v[36:39], v[180:183], v[228:231], v[36:39]
	v_mfma_f32_16x16x32_bf16 v[28:31], v[136:139], v[236:239], v[28:31]
	v_mfma_f32_16x16x32_bf16 v[20:23], v[180:183], v[236:239], v[20:23]
	v_mfma_f32_16x16x32_bf16 v[12:15], v[136:139], v[244:247], v[12:15]
	v_mfma_f32_16x16x32_bf16 v[4:7], v[180:183], v[244:247], v[4:7]
	s_setprio 0
	s_setprio 1
	v_mfma_f32_16x16x32_bf16 v[56:59], v[200:203], v[216:219], v[56:59]
	v_mfma_f32_16x16x32_bf16 v[48:51], v[208:211], v[216:219], v[48:51]
	v_mfma_f32_16x16x32_bf16 v[40:43], v[200:203], v[224:227], v[40:43]
	v_mfma_f32_16x16x32_bf16 v[32:35], v[208:211], v[224:227], v[32:35]
	v_mfma_f32_16x16x32_bf16 v[24:27], v[200:203], v[232:235], v[24:27]
	v_mfma_f32_16x16x32_bf16 v[16:19], v[208:211], v[232:235], v[16:19]
	v_mfma_f32_16x16x32_bf16 v[8:11], v[200:203], v[240:243], v[8:11]
	v_mfma_f32_16x16x32_bf16 v[0:3], v[208:211], v[240:243], v[0:3]
	v_mfma_f32_16x16x32_bf16 v[56:59], v[204:207], v[220:223], v[56:59]
	v_mfma_f32_16x16x32_bf16 v[48:51], v[212:215], v[220:223], v[48:51]
	v_mfma_f32_16x16x32_bf16 v[40:43], v[204:207], v[228:231], v[40:43]
	v_mfma_f32_16x16x32_bf16 v[32:35], v[212:215], v[228:231], v[32:35]
	v_mfma_f32_16x16x32_bf16 v[24:27], v[204:207], v[236:239], v[24:27]
	v_mfma_f32_16x16x32_bf16 v[16:19], v[212:215], v[236:239], v[16:19]
	v_mfma_f32_16x16x32_bf16 v[8:11], v[204:207], v[244:247], v[8:11]
	v_mfma_f32_16x16x32_bf16 v[0:3], v[212:215], v[244:247], v[0:3]
	s_barrier
	s_setprio 0
	s_add_i32 s57, s57, 2
	s_add_u32 s4, s4, 0x100
	s_addc_u32 s5, s5, 0
	s_add_u32 s55, s55, 0x100
	s_addc_u32 s56, s56, 0
	s_cmp_gt_u32 s57, 13
	s_cbranch_scc1 .LBB0_1650
